# nt (non-temporal) hint on once-touched streaming data: x and p reads of the prologue, HB/part reads and d_out stores of the final rmsnorm
# speedup vs baseline: 1.0088x; 1.0088x over previous
; __device__ __forceinline__ unsigned cvt_pk_bf16(float lo, float hi) { unsigned r; asm volatile("v_cvt_pk_bf16_f32 %0, %1, %2" : "=v"(r) : "v"(lo), "v"(hi)); return r; }
; __device__ __forceinline__ void prologue(const Args& A, LAS unsigned char* lds) {
;     ...
;     for (int m = gw; m < MTOK; m += 2 * NGW) {
;         const int m2 = m + NGW; const bool has2 = m2 < MTOK;
;         const f32x4* xr = (const f32x4*)(x + (size_t)m * DM) + lane; const f32x4* xr2 = (const f32x4*)(x + (size_t)(has2 ? m2 : m) * DM) + lane;
;         f32x4 v[4], w[4];
; #pragma unroll
;         for (int j = 0; j < 4; ++j) { v[j] = xr[64 * j]; w[j] = xr2[64 * j]; }
;         float s = 0.f, s2 = 0.f;
;         unsigned long long* o8 = (unsigned long long*)(hb + (size_t)m * DM) + lane; unsigned long long* o82 = (unsigned long long*)(hb + (size_t)(has2 ? m2 : m) * DM) + lane;
; #pragma unroll
;         for (int j = 0; j < 4; ++j) { s += (v[j][0] * v[j][0] + v[j][1] * v[j][1]) + (v[j][2] * v[j][2] + v[j][3] * v[j][3]); s2 += (w[j][0] * w[j][0] + w[j][1] * w[j][1]) + (w[j][2] * w[j][2] + w[j][3] * w[j][3]);
;             o8[64 * j] = (unsigned long long)pg8::cvt_pk_bf16(v[j][0], v[j][1]) | ((unsigned long long)pg8::cvt_pk_bf16(v[j][2], v[j][3]) << 32);
;             if (has2) o82[64 * j] = (unsigned long long)pg8::cvt_pk_bf16(w[j][0], w[j][1]) | ((unsigned long long)pg8::cvt_pk_bf16(w[j][2], w[j][3]) << 32); }
.LBB0_195:
	v_add_u32_e32 v40, s83, v68
	v_cmp_gt_i32_e64 s[4:5], s3, v40
	v_ashrrev_i32_e32 v69, 31, v68
	s_waitcnt lgkmcnt(0)
	v_lshlrev_b64 v[2:3], 12, v[68:69]
	v_cndmask_b32_e64 v48, v68, v40, s[4:5]
	v_ashrrev_i32_e32 v49, 31, v48
	v_lshl_add_u64 v[42:43], v[34:35], 0, v[2:3]
	v_lshlrev_b64 v[2:3], 12, v[48:49]
	v_lshl_add_u64 v[44:45], v[34:35], 0, v[2:3]
	global_load_dwordx4 v[26:29], v[42:43], off nt
	global_load_dwordx4 v[22:25], v[42:43], off offset:1024 nt
	global_load_dwordx4 v[30:33], v[44:45], off nt
	global_load_dwordx4 v[18:21], v[44:45], off offset:1024 nt
	global_load_dwordx4 v[14:17], v[42:43], off offset:2048 nt
	global_load_dwordx4 v[6:9], v[42:43], off offset:3072 nt
	global_load_dwordx4 v[10:13], v[44:45], off offset:2048 nt
	global_load_dwordx4 v[2:5], v[44:45], off offset:3072 nt
	v_lshlrev_b64 v[42:43], 11, v[68:69]
	v_lshl_add_u64 v[44:45], v[36:37], 0, v[42:43]
	v_lshlrev_b64 v[42:43], 11, v[48:49]
	v_lshl_add_u64 v[42:43], v[36:37], 0, v[42:43]
	s_waitcnt vmcnt(7)
	v_cvt_pk_bf16_f32 v48, v26, v27
	v_cvt_pk_bf16_f32 v49, v28, v29
	global_store_dwordx2 v[44:45], v[48:49], off
	s_and_saveexec_b64 s[6:7], s[4:5]
	s_cbranch_execz .LBB0_197
	s_waitcnt vmcnt(6)
	v_cvt_pk_bf16_f32 v48, v30, v31
	v_cvt_pk_bf16_f32 v49, v32, v33
	global_store_dwordx2 v[42:43], v[48:49], off

; __device__ __forceinline__ unsigned cvt_pk_bf16(float lo, float hi) { unsigned r; asm volatile("v_cvt_pk_bf16_f32 %0, %1, %2" : "=v"(r) : "v"(lo), "v"(hi)); return r; }
; __device__ __forceinline__ void prologue(const Args& A, LAS unsigned char* lds) {
;     ...
;     for (size_t i = (size_t)blockIdx.x * 512 + tid; i < n8; i += stride) {
;         const f32x4 a = *(const f32x4*)(p + i * 8), b = *(const f32x4*)(p + i * 8 + 4);
;         u32x4 w; w.x = pg8::cvt_pk_bf16(a[0], a[1]); w.y = pg8::cvt_pk_bf16(a[2], a[3]); w.z = pg8::cvt_pk_bf16(b[0], b[1]); w.w = pg8::cvt_pk_bf16(b[2], b[3]);
;         *(u32x4*)(pb + i * 8) = w;
;     }
.LBB0_208:
	global_load_dwordx4 v[8:11], v[4:5], off offset:-16 nt
	global_load_dwordx4 v[12:15], v[4:5], off nt
	v_lshl_add_u64 v[2:3], v[2:3], 0, s[4:5]
	v_cmp_lt_u64_e32 vcc, s[12:13], v[2:3]
	v_lshl_add_u64 v[4:5], v[4:5], 0, s[6:7]
	s_or_b64 s[10:11], vcc, s[10:11]
	s_waitcnt vmcnt(1)
	v_cvt_pk_bf16_f32 v8, v8, v9
	v_cvt_pk_bf16_f32 v9, v10, v11
	s_waitcnt vmcnt(0)
	v_cvt_pk_bf16_f32 v10, v12, v13
	v_cvt_pk_bf16_f32 v11, v14, v15
	global_store_dwordx4 v[6:7], v[8:11], off
	v_lshl_add_u64 v[6:7], v[6:7], 0, s[8:9]
	s_andn2_b64 exec, exec, s[10:11]
	s_cbranch_execnz .LBB0_208

; __device__ __forceinline__ float bf_lo(unsigned w) { return __uint_as_float(w << 16); }
; __device__ __forceinline__ float bf_hi(unsigned w) { return __uint_as_float(w & 0xffff0000u); }
; __device__ __forceinline__ float row_rinv(const float* part, int row) {
;     const f32x4* p = (const f32x4*)(part + (size_t)row * 16);
;     const f32x4 s = (p[0] + p[1]) + (p[2] + p[3]);
;     return __builtin_amdgcn_rsqf(((s[0] + s[1]) + (s[2] + s[3])) * (1.0f / 1024.0f) + EPS);
; }
; __global__ void __launch_bounds__(512, 2) mega(Args A) {
;     ...
;         for (int m = m0; m < m1; m += 4 * ms) {
;             float rinv[4]; unsigned long long w[4][4];
; #pragma unroll
;             for (int q = 0; q < 4; ++q) { const int mq = (m + q * ms < m1) ? m + q * ms : m; rinv[q] = row_rinv(pr, mq);
;                 const unsigned long long* hr = (const unsigned long long*)(HB0 + (size_t)mq * DM) + lane;
; #pragma unroll
;                 for (int j = 0; j < 4; ++j) w[q][j] = hr[64 * j]; }
; #pragma unroll
;             for (int q = 0; q < 4; ++q) if (m + q * ms < m1) { f32x4* orow = (f32x4*)(A.out + (size_t)(m + q * ms) * DM) + lane;
; #pragma unroll
;                 for (int j = 0; j < 4; ++j) { const unsigned lo = (unsigned)w[q][j], hi = (unsigned)(w[q][j] >> 32);
;                     const f32x4 v = {bf_lo(lo), bf_hi(lo), bf_lo(hi), bf_hi(hi)}; orow[64 * j] = v * rinv[q] * gv[j]; } }
.LBB0_626:
	v_ashrrev_i32_e32 v65, 31, v64
	v_lshlrev_b64 v[18:19], 6, v[64:65]
	v_lshl_add_u64 v[18:19], s[80:81], 0, v[18:19]
	global_load_dwordx4 v[102:105], v[18:19], off offset:32 nt
	global_load_dwordx4 v[106:109], v[18:19], off offset:48 nt
	global_load_dwordx4 v[110:113], v[18:19], off nt
	global_load_dwordx4 v[114:117], v[18:19], off offset:16 nt
	v_add_u32_e32 v90, s8, v64
	v_cmp_gt_i32_e64 s[2:3], s9, v90
	v_lshlrev_b64 v[18:19], 11, v[64:65]
	v_lshl_add_u64 v[18:19], v[66:67], 0, v[18:19]
	v_cndmask_b32_e64 v16, v64, v90, s[2:3]
	v_ashrrev_i32_e32 v17, 31, v16
	global_load_dwordx2 v[118:119], v[18:19], off offset:1536 nt
	global_load_dwordx2 v[120:121], v[18:19], off offset:1024 nt
	global_load_dwordx2 v[122:123], v[18:19], off offset:512 nt
	global_load_dwordx2 v[124:125], v[18:19], off nt
	v_lshlrev_b64 v[18:19], 6, v[16:17]
	v_lshlrev_b64 v[16:17], 11, v[16:17]
	v_add_u32_e32 v86, s11, v64
	v_lshl_add_u64 v[18:19], s[80:81], 0, v[18:19]
	v_lshl_add_u64 v[16:17], v[66:67], 0, v[16:17]
	v_cmp_gt_i32_e64 s[0:1], s9, v86
	global_load_dwordx4 v[48:51], v[18:19], off offset:48 nt
	global_load_dwordx4 v[52:55], v[18:19], off offset:32 nt
	global_load_dwordx4 v[56:59], v[18:19], off offset:16 nt
	global_load_dwordx4 v[60:63], v[18:19], off nt
	global_load_dwordx2 v[98:99], v[16:17], off nt
	global_load_dwordx2 v[96:97], v[16:17], off offset:512 nt
	global_load_dwordx2 v[94:95], v[16:17], off offset:1024 nt
	global_load_dwordx2 v[92:93], v[16:17], off offset:1536 nt
	v_cndmask_b32_e64 v16, v64, v86, s[0:1]
	v_add_u32_e32 v76, s12, v64
	v_ashrrev_i32_e32 v17, 31, v16
	v_cmp_gt_i32_e32 vcc, s9, v76
	v_lshlrev_b64 v[18:19], 6, v[16:17]
	v_lshlrev_b64 v[16:17], 11, v[16:17]
	v_cndmask_b32_e32 v70, v64, v76, vcc
	v_lshl_add_u64 v[18:19], s[80:81], 0, v[18:19]
	v_lshl_add_u64 v[16:17], v[66:67], 0, v[16:17]
	v_ashrrev_i32_e32 v71, 31, v70
	global_load_dwordx4 v[32:35], v[18:19], off offset:48 nt
	global_load_dwordx4 v[36:39], v[18:19], off offset:32 nt
	global_load_dwordx4 v[40:43], v[18:19], off offset:16 nt
	global_load_dwordx4 v[44:47], v[18:19], off nt
	global_load_dwordx2 v[88:89], v[16:17], off nt
	global_load_dwordx2 v[84:85], v[16:17], off offset:512 nt
	global_load_dwordx2 v[82:83], v[16:17], off offset:1024 nt
	global_load_dwordx2 v[80:81], v[16:17], off offset:1536 nt
	v_lshlrev_b64 v[16:17], 6, v[70:71]
	v_lshlrev_b64 v[70:71], 11, v[70:71]
	v_lshl_add_u64 v[72:73], s[80:81], 0, v[16:17]
	v_lshl_add_u64 v[126:127], v[66:67], 0, v[70:71]
	global_load_dwordx4 v[16:19], v[72:73], off offset:48 nt
	global_load_dwordx4 v[20:23], v[72:73], off offset:32 nt
	global_load_dwordx4 v[24:27], v[72:73], off offset:16 nt
	global_load_dwordx4 v[28:31], v[72:73], off nt
	global_load_dwordx2 v[78:79], v[126:127], off nt
	global_load_dwordx2 v[74:75], v[126:127], off offset:512 nt
	s_nop 0
	global_load_dwordx2 v[72:73], v[126:127], off offset:1024 nt
	global_load_dwordx2 v[70:71], v[126:127], off offset:1536 nt
	v_lshlrev_b64 v[126:127], 12, v[64:65]
	v_lshl_add_u64 v[126:127], v[68:69], 0, v[126:127]
	s_waitcnt vmcnt(0)
	v_pk_add_f32 v[104:105], v[104:105], v[108:109]
	v_pk_add_f32 v[102:103], v[102:103], v[106:107]
	v_pk_add_f32 v[112:113], v[112:113], v[116:117]
	v_pk_add_f32 v[110:111], v[110:111], v[114:115]
	v_pk_add_f32 v[104:105], v[112:113], v[104:105]
	v_pk_add_f32 v[102:103], v[110:111], v[102:103]
	v_lshlrev_b32_e32 v112, 16, v120
	v_pk_mov_b32 v[110:111], v[102:103], v[104:105] op_sel:[1,0]
	v_mov_b32_e32 v103, v105
	v_pk_add_f32 v[102:103], v[110:111], v[102:103]
	v_lshlrev_b32_e32 v106, 16, v124
	v_add_f32_e32 v65, v102, v103
	v_fmamk_f32 v65, v65, 0x3a800000, v100
	v_rsq_f32_e32 v110, v65
	v_and_b32_e32 v107, 0xffff0000, v124
	v_lshlrev_b32_e32 v108, 16, v125
	v_and_b32_e32 v109, 0xffff0000, v125
	v_lshlrev_b32_e32 v114, 16, v122
	v_and_b32_e32 v115, 0xffff0000, v122
	v_lshlrev_b32_e32 v116, 16, v123
	v_and_b32_e32 v117, 0xffff0000, v123
	v_pk_mul_f32 v[102:103], v[110:111], v[106:107] op_sel_hi:[0,1]
	v_pk_mul_f32 v[104:105], v[110:111], v[108:109] op_sel_hi:[0,1]
	v_and_b32_e32 v113, 0xffff0000, v120
	v_lshlrev_b32_e32 v120, 16, v121
	v_pk_mul_f32 v[106:107], v[110:111], v[114:115] op_sel_hi:[0,1]
	v_pk_mul_f32 v[108:109], v[110:111], v[116:117] op_sel_hi:[0,1]
	v_pk_mul_f32 v[104:105], v[2:3], v[104:105]
	v_pk_mul_f32 v[102:103], v[0:1], v[102:103]
	v_and_b32_e32 v121, 0xffff0000, v121
	v_pk_mul_f32 v[108:109], v[6:7], v[108:109]
	v_pk_mul_f32 v[106:107], v[4:5], v[106:107]
	global_store_dwordx4 v[126:127], v[102:105], off nt
	global_store_dwordx4 v[126:127], v[106:109], off offset:1024 nt
	s_nop 0
	v_pk_mul_f32 v[102:103], v[110:111], v[112:113] op_sel_hi:[0,1]
	v_pk_mul_f32 v[104:105], v[110:111], v[120:121] op_sel_hi:[0,1]
	v_pk_mul_f32 v[104:105], v[10:11], v[104:105]
	v_pk_mul_f32 v[102:103], v[8:9], v[102:103]
	global_store_dwordx4 v[126:127], v[102:105], off offset:2048 nt
	s_nop 1
	v_lshlrev_b32_e32 v102, 16, v118
	v_and_b32_e32 v103, 0xffff0000, v118
	v_lshlrev_b32_e32 v104, 16, v119
	v_and_b32_e32 v105, 0xffff0000, v119
	v_pk_mul_f32 v[102:103], v[110:111], v[102:103] op_sel_hi:[0,1]
	v_pk_mul_f32 v[104:105], v[110:111], v[104:105] op_sel_hi:[0,1]
	v_pk_mul_f32 v[104:105], v[14:15], v[104:105]
	v_pk_mul_f32 v[102:103], v[12:13], v[102:103]
	global_store_dwordx4 v[126:127], v[102:105], off offset:3072 nt
	s_and_saveexec_b64 s[6:7], s[2:3]
	s_cbranch_execnz .LBB0_629
	s_or_b64 exec, exec, s[6:7]
	s_and_saveexec_b64 s[2:3], s[0:1]
	s_cbranch_execnz .LBB0_630

; __device__ __forceinline__ float bf_lo(unsigned w) { return __uint_as_float(w << 16); }
; __device__ __forceinline__ float bf_hi(unsigned w) { return __uint_as_float(w & 0xffff0000u); }
; __global__ void __launch_bounds__(512, 2) mega(Args A) {
;     ...
;             for (int q = 0; q < 4; ++q) if (m + q * ms < m1) { f32x4* orow = (f32x4*)(A.out + (size_t)(m + q * ms) * DM) + lane;
; #pragma unroll
;                 for (int j = 0; j < 4; ++j) { const unsigned lo = (unsigned)w[q][j], hi = (unsigned)(w[q][j] >> 32);
;                     const f32x4 v = {bf_lo(lo), bf_hi(lo), bf_lo(hi), bf_hi(hi)}; orow[64 * j] = v * rinv[q] * gv[j]; } }
.LBB0_629:
	v_pk_add_f32 v[58:59], v[62:63], v[58:59]
	v_pk_add_f32 v[56:57], v[60:61], v[56:57]
	v_pk_add_f32 v[48:49], v[52:53], v[48:49]
	v_pk_add_f32 v[50:51], v[54:55], v[50:51]
	v_pk_add_f32 v[48:49], v[56:57], v[48:49]
	v_pk_add_f32 v[50:51], v[58:59], v[50:51]
	v_ashrrev_i32_e32 v91, 31, v90
	v_pk_mov_b32 v[52:53], v[48:49], v[50:51] op_sel:[1,0]
	v_mov_b32_e32 v49, v51
	v_pk_add_f32 v[48:49], v[52:53], v[48:49]
	v_lshlrev_b32_e32 v50, 16, v99
	v_add_f32_e32 v48, v48, v49
	v_fmamk_f32 v48, v48, 0x3a800000, v100
	v_rsq_f32_e32 v52, v48
	v_lshlrev_b64 v[48:49], 12, v[90:91]
	v_lshl_add_u64 v[54:55], v[68:69], 0, v[48:49]
	v_lshlrev_b32_e32 v48, 16, v98
	v_and_b32_e32 v49, 0xffff0000, v98
	v_and_b32_e32 v51, 0xffff0000, v99
	v_pk_mul_f32 v[48:49], v[52:53], v[48:49] op_sel_hi:[0,1]
	v_pk_mul_f32 v[50:51], v[52:53], v[50:51] op_sel_hi:[0,1]
	v_pk_mul_f32 v[50:51], v[2:3], v[50:51]
	v_pk_mul_f32 v[48:49], v[0:1], v[48:49]
	global_store_dwordx4 v[54:55], v[48:51], off nt
	s_nop 1
	v_lshlrev_b32_e32 v48, 16, v96
	v_and_b32_e32 v49, 0xffff0000, v96
	v_lshlrev_b32_e32 v50, 16, v97
	v_and_b32_e32 v51, 0xffff0000, v97
	v_pk_mul_f32 v[48:49], v[52:53], v[48:49] op_sel_hi:[0,1]
	v_pk_mul_f32 v[50:51], v[52:53], v[50:51] op_sel_hi:[0,1]
	v_pk_mul_f32 v[50:51], v[6:7], v[50:51]
	v_pk_mul_f32 v[48:49], v[4:5], v[48:49]
	global_store_dwordx4 v[54:55], v[48:51], off offset:1024 nt
	s_nop 1
	v_lshlrev_b32_e32 v48, 16, v94
	v_and_b32_e32 v49, 0xffff0000, v94
	v_lshlrev_b32_e32 v50, 16, v95
	v_and_b32_e32 v51, 0xffff0000, v95
	v_pk_mul_f32 v[48:49], v[52:53], v[48:49] op_sel_hi:[0,1]
	v_pk_mul_f32 v[50:51], v[52:53], v[50:51] op_sel_hi:[0,1]
	v_pk_mul_f32 v[50:51], v[10:11], v[50:51]
	v_pk_mul_f32 v[48:49], v[8:9], v[48:49]
	global_store_dwordx4 v[54:55], v[48:51], off offset:2048 nt
	s_nop 1
	v_lshlrev_b32_e32 v48, 16, v92
	v_and_b32_e32 v49, 0xffff0000, v92
	v_lshlrev_b32_e32 v50, 16, v93
	v_and_b32_e32 v51, 0xffff0000, v93
	v_pk_mul_f32 v[48:49], v[52:53], v[48:49] op_sel_hi:[0,1]
	v_pk_mul_f32 v[50:51], v[52:53], v[50:51] op_sel_hi:[0,1]
	v_pk_mul_f32 v[50:51], v[14:15], v[50:51]
	v_pk_mul_f32 v[48:49], v[12:13], v[48:49]
	global_store_dwordx4 v[54:55], v[48:51], off offset:3072 nt
	s_or_b64 exec, exec, s[6:7]
	s_and_saveexec_b64 s[2:3], s[0:1]
	s_cbranch_execz .LBB0_628
.LBB0_630:
	v_pk_add_f32 v[42:43], v[46:47], v[42:43]
	v_pk_add_f32 v[40:41], v[44:45], v[40:41]
	v_pk_add_f32 v[32:33], v[36:37], v[32:33]
	v_pk_add_f32 v[34:35], v[38:39], v[34:35]
	v_pk_add_f32 v[32:33], v[40:41], v[32:33]
	v_pk_add_f32 v[34:35], v[42:43], v[34:35]
	v_add_f32_e32 v32, v32, v33
	v_add_f32_e32 v33, v34, v35
	v_add_f32_e32 v32, v32, v33
	v_fmamk_f32 v32, v32, 0x3a800000, v100
	v_rsq_f32_e32 v36, v32
	v_ashrrev_i32_e32 v87, 31, v86
	v_lshlrev_b64 v[32:33], 12, v[86:87]
	v_lshl_add_u64 v[38:39], v[68:69], 0, v[32:33]
	v_lshlrev_b32_e32 v32, 16, v88
	v_and_b32_e32 v33, 0xffff0000, v88
	v_lshlrev_b32_e32 v34, 16, v89
	v_and_b32_e32 v35, 0xffff0000, v89
	v_pk_mul_f32 v[32:33], v[36:37], v[32:33] op_sel_hi:[0,1]
	v_pk_mul_f32 v[34:35], v[36:37], v[34:35] op_sel_hi:[0,1]
	v_pk_mul_f32 v[34:35], v[2:3], v[34:35]
	v_pk_mul_f32 v[32:33], v[0:1], v[32:33]
	global_store_dwordx4 v[38:39], v[32:35], off nt
	s_nop 1
	v_lshlrev_b32_e32 v32, 16, v84
	v_and_b32_e32 v33, 0xffff0000, v84
	v_lshlrev_b32_e32 v34, 16, v85
	v_and_b32_e32 v35, 0xffff0000, v85
	v_pk_mul_f32 v[32:33], v[36:37], v[32:33] op_sel_hi:[0,1]
	v_pk_mul_f32 v[34:35], v[36:37], v[34:35] op_sel_hi:[0,1]
	v_pk_mul_f32 v[34:35], v[6:7], v[34:35]
	v_pk_mul_f32 v[32:33], v[4:5], v[32:33]
	global_store_dwordx4 v[38:39], v[32:35], off offset:1024 nt
	s_nop 1
	v_lshlrev_b32_e32 v32, 16, v82
	v_and_b32_e32 v33, 0xffff0000, v82
	v_lshlrev_b32_e32 v34, 16, v83
	v_and_b32_e32 v35, 0xffff0000, v83
	v_pk_mul_f32 v[32:33], v[36:37], v[32:33] op_sel_hi:[0,1]
	v_pk_mul_f32 v[34:35], v[36:37], v[34:35] op_sel_hi:[0,1]
	v_pk_mul_f32 v[34:35], v[10:11], v[34:35]
	v_pk_mul_f32 v[32:33], v[8:9], v[32:33]
	global_store_dwordx4 v[38:39], v[32:35], off offset:2048 nt
	s_nop 1
	v_lshlrev_b32_e32 v32, 16, v80
	v_and_b32_e32 v33, 0xffff0000, v80
	v_lshlrev_b32_e32 v34, 16, v81
	v_and_b32_e32 v35, 0xffff0000, v81
	v_pk_mul_f32 v[32:33], v[36:37], v[32:33] op_sel_hi:[0,1]
	v_pk_mul_f32 v[34:35], v[36:37], v[34:35] op_sel_hi:[0,1]
	v_pk_mul_f32 v[34:35], v[14:15], v[34:35]
	v_pk_mul_f32 v[32:33], v[12:13], v[32:33]
	global_store_dwordx4 v[38:39], v[32:35], off offset:3072 nt
	s_or_b64 exec, exec, s[2:3]
	s_and_saveexec_b64 s[0:1], vcc
	s_cbranch_execz .LBB0_625
.LBB0_631:
	v_pk_add_f32 v[26:27], v[30:31], v[26:27]
	v_pk_add_f32 v[24:25], v[28:29], v[24:25]
	v_pk_add_f32 v[16:17], v[20:21], v[16:17]
	v_pk_add_f32 v[18:19], v[22:23], v[18:19]
	v_pk_add_f32 v[16:17], v[24:25], v[16:17]
	v_pk_add_f32 v[18:19], v[26:27], v[18:19]
	v_add_f32_e32 v16, v16, v17
	v_add_f32_e32 v17, v18, v19
	v_add_f32_e32 v16, v16, v17
	v_fmamk_f32 v16, v16, 0x3a800000, v100
	v_rsq_f32_e32 v20, v16
	v_ashrrev_i32_e32 v77, 31, v76
	v_lshlrev_b64 v[16:17], 12, v[76:77]
	v_lshl_add_u64 v[22:23], v[68:69], 0, v[16:17]
	v_lshlrev_b32_e32 v16, 16, v78
	v_and_b32_e32 v17, 0xffff0000, v78
	v_lshlrev_b32_e32 v18, 16, v79
	v_and_b32_e32 v19, 0xffff0000, v79
	v_pk_mul_f32 v[16:17], v[20:21], v[16:17] op_sel_hi:[0,1]
	v_pk_mul_f32 v[18:19], v[20:21], v[18:19] op_sel_hi:[0,1]
	v_pk_mul_f32 v[18:19], v[2:3], v[18:19]
	v_pk_mul_f32 v[16:17], v[0:1], v[16:17]
	global_store_dwordx4 v[22:23], v[16:19], off nt
	s_nop 1
	v_lshlrev_b32_e32 v16, 16, v74
	v_and_b32_e32 v17, 0xffff0000, v74
	v_lshlrev_b32_e32 v18, 16, v75
	v_and_b32_e32 v19, 0xffff0000, v75
	v_pk_mul_f32 v[16:17], v[20:21], v[16:17] op_sel_hi:[0,1]
	v_pk_mul_f32 v[18:19], v[20:21], v[18:19] op_sel_hi:[0,1]
	v_pk_mul_f32 v[18:19], v[6:7], v[18:19]
	v_pk_mul_f32 v[16:17], v[4:5], v[16:17]
	global_store_dwordx4 v[22:23], v[16:19], off offset:1024 nt
	s_nop 1
	v_lshlrev_b32_e32 v16, 16, v72
	v_and_b32_e32 v17, 0xffff0000, v72
	v_lshlrev_b32_e32 v18, 16, v73
	v_and_b32_e32 v19, 0xffff0000, v73
	v_pk_mul_f32 v[16:17], v[20:21], v[16:17] op_sel_hi:[0,1]
	v_pk_mul_f32 v[18:19], v[20:21], v[18:19] op_sel_hi:[0,1]
	v_pk_mul_f32 v[18:19], v[10:11], v[18:19]
	v_pk_mul_f32 v[16:17], v[8:9], v[16:17]
	global_store_dwordx4 v[22:23], v[16:19], off offset:2048 nt
	s_nop 1
	v_lshlrev_b32_e32 v16, 16, v70
	v_and_b32_e32 v17, 0xffff0000, v70
	v_lshlrev_b32_e32 v18, 16, v71
	v_and_b32_e32 v19, 0xffff0000, v71
	v_pk_mul_f32 v[16:17], v[20:21], v[16:17] op_sel_hi:[0,1]
	v_pk_mul_f32 v[18:19], v[20:21], v[18:19] op_sel_hi:[0,1]
	v_pk_mul_f32 v[18:19], v[14:15], v[18:19]
	v_pk_mul_f32 v[16:17], v[12:13], v[16:17]
	global_store_dwordx4 v[22:23], v[16:19], off offset:3072 nt
	s_branch .LBB0_625
